# nt loads also for the phase-9 x row stream (x is not reused until the final pass)
# baseline (speedup 1.0000x reference)
.LBB0_1151:
	s_cmp_lt_i32 s92, 10
	s_cselect_b64 s[0:1], -1, 0
	s_and_b64 s[4:5], s[0:1], s[4:5]
	s_andn2_b64 vcc, exec, s[4:5]
	v_lshrrev_b32_e32 v161, 6, v160
	s_cbranch_vccnz .LBB0_1182
	s_lshl_b32 s4, s34, 3
	s_abs_i32 s5, s4
	v_cvt_f32_u32_e32 v0, s5
	s_add_i32 s6, s4, 0x7fff
	s_sub_i32 s7, 0xffff8001, s4
	s_xor_b32 s4, s6, s4
	v_rcp_iflag_f32_e32 v0, v0
	s_max_i32 s6, s6, s7
	s_sub_i32 s7, 0, s5
	s_ashr_i32 s4, s4, 31
	v_mul_f32_e32 v0, 0x4f7ffffe, v0
	v_cvt_u32_f32_e32 v0, v0
	v_lshl_add_u32 v1, s20, 3, v161
	v_readfirstlane_b32 s8, v0
	s_mul_i32 s7, s7, s8
	s_mul_hi_u32 s7, s8, s7
	s_add_i32 s8, s8, s7
	s_mul_hi_u32 s7, s6, s8
	s_mul_i32 s8, s7, s5
	s_sub_i32 s6, s6, s8
	s_add_i32 s9, s7, 1
	s_sub_i32 s8, s6, s5
	s_cmp_ge_u32 s6, s5
	s_cselect_b32 s7, s9, s7
	s_cselect_b32 s6, s8, s6
	s_add_i32 s8, s7, 1
	s_cmp_ge_u32 s6, s5
	s_cselect_b32 s5, s8, s7
	s_xor_b32 s5, s5, s4
	s_sub_i32 s4, s5, s4
	v_mul_lo_u32 v48, s4, v1
	v_add_u32_e32 v0, s4, v48
	v_min_i32_e32 v123, 0x8000, v0
	v_cmp_lt_i32_e32 vcc, v48, v123
	s_and_saveexec_b64 s[6:7], vcc
	s_cbranch_execz .LBB0_1181
	v_ashrrev_i32_e32 v49, 31, v48
	v_readlane_b32 s36, v240, 8
	v_lshlrev_b32_e32 v4, 2, v160
	s_add_u32 s4, s22, 0x154bc000
	v_lshlrev_b64 v[0:1], 12, v[48:49]
	v_readlane_b32 s37, v240, 9
	v_lshlrev_b64 v[50:51], 11, v[48:49]
	v_and_b32_e32 v49, 0xfc, v4
	s_addc_u32 s5, s23, 0
	v_lshl_add_u64 v[0:1], s[36:37], 0, v[0:1]
	v_mov_b32_e32 v97, 0
	v_lshlrev_b32_e32 v96, 2, v49
	v_lshl_add_u64 v[2:3], s[4:5], 0, v[50:51]
	v_lshl_add_u64 v[16:17], v[0:1], 0, v[96:97]
	v_lshlrev_b32_e32 v52, 1, v49
	v_mov_b32_e32 v53, v97
	v_lshl_add_u64 v[18:19], v[2:3], 0, v[52:53]
	global_load_dwordx4 v[0:3], v[16:17], off nt
	global_load_dwordx4 v[4:7], v[16:17], off offset:1024 nt
	global_load_dwordx2 v[98:99], v[18:19], off
	global_load_dwordx2 v[100:101], v[18:19], off offset:512
	global_load_dwordx2 v[102:103], v[18:19], off offset:1024
	global_load_dwordx2 v[104:105], v[18:19], off offset:1536
	global_load_dwordx4 v[8:11], v[16:17], off offset:2048 nt
	global_load_dwordx4 v[12:15], v[16:17], off offset:3072 nt
	v_add_u32_e32 v32, 1, v48
	v_cmp_lt_i32_e32 vcc, v32, v123
	v_readlane_b32 s38, v240, 10
	v_readlane_b32 s39, v240, 11
	v_readlane_b32 s40, v240, 12
	v_readlane_b32 s41, v240, 13
	v_readlane_b32 s42, v240, 14
	v_readlane_b32 s43, v240, 15
	v_readlane_b32 s44, v240, 16
	v_readlane_b32 s45, v240, 17
	v_readlane_b32 s46, v240, 18
	v_readlane_b32 s47, v240, 19
	v_readlane_b32 s48, v240, 20
	v_readlane_b32 s49, v240, 21
	v_readlane_b32 s50, v240, 22
	v_readlane_b32 s51, v240, 23
	s_and_saveexec_b64 s[8:9], vcc
	s_cbranch_execz .LBB0_1155
	v_ashrrev_i32_e32 v33, 31, v32
	v_readlane_b32 s36, v240, 8
	v_lshlrev_b64 v[16:17], 12, v[32:33]
	v_readlane_b32 s37, v240, 9
	v_lshlrev_b64 v[18:19], 11, v[32:33]
	v_lshl_add_u64 v[18:19], s[4:5], 0, v[18:19]
	v_lshl_add_u64 v[16:17], s[36:37], 0, v[16:17]
	v_lshl_add_u64 v[32:33], v[16:17], 0, v[96:97]
	v_lshl_add_u64 v[34:35], v[18:19], 0, v[52:53]
	global_load_dwordx4 v[16:19], v[32:33], off nt
	global_load_dwordx4 v[20:23], v[32:33], off offset:1024 nt
	global_load_dwordx4 v[24:27], v[32:33], off offset:2048 nt
	global_load_dwordx4 v[28:31], v[32:33], off offset:3072 nt
	global_load_dwordx2 v[106:107], v[34:35], off
	global_load_dwordx2 v[108:109], v[34:35], off offset:512
	global_load_dwordx2 v[110:111], v[34:35], off offset:1024
	global_load_dwordx2 v[112:113], v[34:35], off offset:1536
	v_readlane_b32 s38, v240, 10
	v_readlane_b32 s39, v240, 11
	v_readlane_b32 s40, v240, 12
	v_readlane_b32 s41, v240, 13
	v_readlane_b32 s42, v240, 14
	v_readlane_b32 s43, v240, 15
	v_readlane_b32 s44, v240, 16
	v_readlane_b32 s45, v240, 17
	v_readlane_b32 s46, v240, 18
	v_readlane_b32 s47, v240, 19
	v_readlane_b32 s48, v240, 20
	v_readlane_b32 s49, v240, 21
	v_readlane_b32 s50, v240, 22
	v_readlane_b32 s51, v240, 23
.LBB0_1155:
	s_or_b64 exec, exec, s[8:9]
	v_add_u32_e32 v54, 2, v48
	v_cmp_lt_i32_e32 vcc, v54, v123
	s_and_saveexec_b64 s[8:9], vcc
	s_cbranch_execz .LBB0_1157
	v_ashrrev_i32_e32 v55, 31, v54
	v_readlane_b32 s36, v240, 8
	v_lshlrev_b64 v[32:33], 12, v[54:55]
	v_readlane_b32 s37, v240, 9
	v_lshlrev_b64 v[34:35], 11, v[54:55]
	v_mov_b32_e32 v97, 0
	v_lshl_add_u64 v[32:33], s[36:37], 0, v[32:33]
	v_lshl_add_u64 v[34:35], s[4:5], 0, v[34:35]
	v_lshl_add_u64 v[54:55], v[32:33], 0, v[96:97]
	v_mov_b32_e32 v53, v97
	v_lshl_add_u64 v[56:57], v[34:35], 0, v[52:53]
	global_load_dwordx4 v[32:35], v[54:55], off nt
	global_load_dwordx4 v[36:39], v[54:55], off offset:1024 nt
	global_load_dwordx4 v[40:43], v[54:55], off offset:2048 nt
	global_load_dwordx4 v[44:47], v[54:55], off offset:3072 nt
	global_load_dwordx2 v[114:115], v[56:57], off
	global_load_dwordx2 v[116:117], v[56:57], off offset:512
	global_load_dwordx2 v[118:119], v[56:57], off offset:1024
	global_load_dwordx2 v[120:121], v[56:57], off offset:1536
	v_readlane_b32 s38, v240, 10
	v_readlane_b32 s39, v240, 11
	v_readlane_b32 s40, v240, 12
	v_readlane_b32 s41, v240, 13
	v_readlane_b32 s42, v240, 14
	v_readlane_b32 s43, v240, 15
	v_readlane_b32 s44, v240, 16
	v_readlane_b32 s45, v240, 17
	v_readlane_b32 s46, v240, 18
	v_readlane_b32 s47, v240, 19
	v_readlane_b32 s48, v240, 20
	v_readlane_b32 s49, v240, 21
	v_readlane_b32 s50, v240, 22
	v_readlane_b32 s51, v240, 23

.LBB0_1160:
	v_add_u32_e32 v154, -3, v140
	v_cmp_lt_i32_e64 s[4:5], v154, v123
	v_ashrrev_i32_e32 v155, 31, v154
	s_and_saveexec_b64 s[16:17], s[4:5]
	s_cbranch_execz .LBB0_1162
	v_lshlrev_b64 v[48:49], 12, v[154:155]
	v_lshl_add_u64 v[60:61], v[132:133], 0, v[48:49]
	v_lshlrev_b64 v[48:49], 11, v[154:155]
	v_lshl_add_u64 v[146:147], v[134:135], 0, v[48:49]
	global_load_dwordx4 v[48:51], v[60:61], off nt
	global_load_dwordx4 v[56:59], v[60:61], off offset:1024 nt
	global_load_dwordx4 v[52:55], v[60:61], off offset:2048 nt
	s_nop 0
	global_load_dwordx4 v[60:63], v[60:61], off offset:3072 nt
	s_nop 0
	global_load_dwordx2 v[152:153], v[146:147], off
	global_load_dwordx2 v[150:151], v[146:147], off offset:512
	global_load_dwordx2 v[148:149], v[146:147], off offset:1024
	s_nop 0
	global_load_dwordx2 v[146:147], v[146:147], off offset:1536
.LBB0_1162:
	s_or_b64 exec, exec, s[16:17]
	v_add_u32_e32 v141, -6, v140
	v_ashrrev_i32_e32 v141, 12, v141
	v_cmp_ne_u32_e32 vcc, v141, v167
	s_and_saveexec_b64 s[16:17], vcc
	s_cbranch_execz .LBB0_1164
	v_mul_hi_i32_i24_e32 v65, 0x6000, v141
	v_mul_i32_i24_e32 v64, 0x6000, v141
	v_lshl_add_u64 v[64:65], s[88:89], 0, v[64:65]
	v_lshl_add_u64 v[66:67], v[64:65], 0, s[10:11]
	v_lshlrev_b32_e32 v68, 2, v122
	v_mov_b32_e32 v69, v97
	v_lshl_add_u64 v[76:77], v[64:65], 0, s[12:13]
	v_lshl_add_u64 v[64:65], v[66:67], 0, v[96:97]
	v_lshl_add_u64 v[70:71], v[66:67], 0, v[68:69]
	v_lshlrev_b32_e32 v72, 2, v124
	v_mov_b32_e32 v73, v97
	global_load_dwordx4 v[80:83], v[64:65], off nt
	global_load_dwordx4 v[84:87], v[70:71], off nt
	v_lshl_add_u64 v[70:71], v[66:67], 0, v[72:73]
	v_lshlrev_b32_e32 v78, 2, v126
	v_mov_b32_e32 v79, v97
	v_lshl_add_u64 v[64:65], v[76:77], 0, v[96:97]
	global_load_dwordx4 v[88:91], v[70:71], off nt
	v_lshl_add_u64 v[66:67], v[66:67], 0, v[78:79]
	v_lshl_add_u64 v[68:69], v[76:77], 0, v[68:69]
	global_load_dwordx4 v[92:95], v[66:67], off nt
	s_nop 0
	global_load_dwordx4 v[64:67], v[64:65], off nt
	s_nop 0
	global_load_dwordx4 v[156:159], v[130:131], off nt
	global_load_dwordx4 v[168:171], v[130:131], off offset:1024 nt
	s_nop 0
	global_load_dwordx4 v[68:71], v[68:69], off nt
	s_nop 0
	global_load_dwordx4 v[172:175], v[130:131], off offset:2048 nt
	v_lshl_add_u64 v[72:73], v[76:77], 0, v[72:73]
	v_lshl_add_u64 v[76:77], v[76:77], 0, v[78:79]
	global_load_dwordx4 v[176:179], v[130:131], off offset:3072 nt
	s_nop 0
	global_load_dwordx4 v[72:75], v[72:73], off nt
	v_mov_b32_e32 v167, v141
	global_load_dwordx4 v[76:79], v[76:77], off nt
	s_waitcnt vmcnt(0)
	v_pk_add_f32 v[82:83], v[82:83], 1.0 op_sel_hi:[1,0]
	v_pk_add_f32 v[80:81], v[80:81], 1.0 op_sel_hi:[1,0]
	v_pk_add_f32 v[86:87], v[86:87], 1.0 op_sel_hi:[1,0]
	v_pk_add_f32 v[84:85], v[84:85], 1.0 op_sel_hi:[1,0]
	v_pk_add_f32 v[90:91], v[90:91], 1.0 op_sel_hi:[1,0]
	v_pk_add_f32 v[88:89], v[88:89], 1.0 op_sel_hi:[1,0]
	v_pk_add_f32 v[94:95], v[94:95], 1.0 op_sel_hi:[1,0]
	v_pk_add_f32 v[92:93], v[92:93], 1.0 op_sel_hi:[1,0]
	v_pk_mul_f32 v[82:83], v[158:159], v[82:83]
	v_pk_mul_f32 v[80:81], v[156:157], v[80:81]
	v_pk_mul_f32 v[86:87], v[170:171], v[86:87]
	v_pk_mul_f32 v[84:85], v[168:169], v[84:85]
	v_pk_mul_f32 v[90:91], v[174:175], v[90:91]
	v_pk_mul_f32 v[88:89], v[172:173], v[88:89]
	v_pk_mul_f32 v[94:95], v[178:179], v[94:95]
	v_pk_mul_f32 v[92:93], v[176:177], v[92:93]
.LBB0_1164:
	s_or_b64 exec, exec, s[16:17]
	s_waitcnt vmcnt(0)
	v_lshlrev_b32_e32 v158, 16, v99
	v_and_b32_e32 v159, 0xffff0000, v99
	v_lshlrev_b32_e32 v156, 16, v98
	v_and_b32_e32 v157, 0xffff0000, v98
	v_pk_add_f32 v[2:3], v[2:3], v[158:159]
	v_lshlrev_b32_e32 v158, 16, v101
	v_and_b32_e32 v159, 0xffff0000, v101
	v_pk_add_f32 v[0:1], v[0:1], v[156:157]
	v_lshlrev_b32_e32 v156, 16, v100
	v_and_b32_e32 v157, 0xffff0000, v100
	v_pk_add_f32 v[6:7], v[6:7], v[158:159]
	v_lshlrev_b32_e32 v158, 16, v103
	v_and_b32_e32 v159, 0xffff0000, v103
	v_pk_add_f32 v[4:5], v[4:5], v[156:157]
	v_lshlrev_b32_e32 v156, 16, v102
	v_and_b32_e32 v157, 0xffff0000, v102
	v_pk_add_f32 v[10:11], v[10:11], v[158:159]
	v_lshlrev_b32_e32 v158, 16, v105
	v_and_b32_e32 v159, 0xffff0000, v105
	v_pk_add_f32 v[8:9], v[8:9], v[156:157]
	v_lshlrev_b32_e32 v156, 16, v104
	v_and_b32_e32 v157, 0xffff0000, v104
	v_pk_add_f32 v[14:15], v[14:15], v[158:159]
	v_mov_b32_e32 v158, v5
	v_mov_b32_e32 v159, v1
	v_pk_add_f32 v[12:13], v[12:13], v[156:157]
	v_mov_b32_e32 v156, v4
	v_mov_b32_e32 v157, v0
	v_pk_mul_f32 v[158:159], v[158:159], v[158:159]
	v_mov_b32_e32 v168, v13
	v_pk_fma_f32 v[156:157], v[156:157], v[156:157], v[158:159]
	v_mov_b32_e32 v158, v6
	v_mov_b32_e32 v159, v2
	v_pk_fma_f32 v[156:157], v[158:159], v[158:159], v[156:157]
	v_mov_b32_e32 v158, v7
	v_mov_b32_e32 v159, v3
	v_mov_b32_e32 v169, v9
	v_pk_fma_f32 v[156:157], v[158:159], v[158:159], v[156:157]
	v_mov_b32_e32 v158, v12
	v_mov_b32_e32 v159, v8
	v_pk_mul_f32 v[168:169], v[168:169], v[168:169]
	v_add_f32_e32 v141, v156, v157
	v_pk_fma_f32 v[158:159], v[158:159], v[158:159], v[168:169]
	v_mov_b32_e32 v168, v14
	v_mov_b32_e32 v169, v10
	v_pk_fma_f32 v[158:159], v[168:169], v[168:169], v[158:159]
	v_mov_b32_e32 v168, v15
	v_mov_b32_e32 v169, v11
	v_pk_fma_f32 v[158:159], v[168:169], v[168:169], v[158:159]
	s_nop 0
	v_add_f32_e32 v141, v159, v141
	v_add_f32_e32 v141, v158, v141
	ds_bpermute_b32 v156, v125, v141
	v_lshl_add_u64 v[158:159], v[144:145], 0, v[136:137]
	s_waitcnt lgkmcnt(0)
	v_add_f32_e32 v141, v141, v156
	ds_bpermute_b32 v156, v127, v141
	s_waitcnt lgkmcnt(0)
	v_add_f32_e32 v141, v141, v156
	ds_bpermute_b32 v156, v162, v141
	s_waitcnt lgkmcnt(0)
	v_add_f32_e32 v141, v141, v156
	ds_bpermute_b32 v156, v163, v141
	s_waitcnt lgkmcnt(0)
	v_add_f32_e32 v141, v141, v156
	ds_bpermute_b32 v156, v164, v141
	s_waitcnt lgkmcnt(0)
	v_add_f32_e32 v141, v141, v156
	ds_bpermute_b32 v156, v165, v141
	s_waitcnt lgkmcnt(0)
	v_add_f32_e32 v141, v141, v156
	v_fmamk_f32 v141, v141, 0x3a800000, v166
	v_mul_f32_e32 v156, 0x4b800000, v141
	v_cmp_gt_f32_e32 vcc, s26, v141
	s_nop 1
	v_cndmask_b32_e32 v141, v141, v156, vcc
	v_rsq_f32_e32 v141, v141
	s_nop 0
	v_mul_f32_e32 v156, 0x45800000, v141
	v_cndmask_b32_e32 v156, v141, v156, vcc
	v_pk_mul_f32 v[168:169], v[0:1], v[156:157] op_sel_hi:[1,0]
	v_pk_mul_f32 v[170:171], v[2:3], v[156:157] op_sel_hi:[1,0]
	v_pk_fma_f32 v[168:169], v[80:81], v[168:169], v[64:65]
	v_pk_fma_f32 v[170:171], v[82:83], v[170:171], v[66:67]
	v_add_co_u32_e32 v158, vcc, s27, v158
	v_cvt_pk_bf16_f32 v168, v168, v169
	v_cvt_pk_bf16_f32 v169, v170, v171
	v_addc_co_u32_e32 v159, vcc, 0, v159, vcc
	global_store_dwordx2 v[158:159], v[168:169], off
	v_pk_mul_f32 v[168:169], v[4:5], v[156:157] op_sel_hi:[1,0]
	v_pk_mul_f32 v[170:171], v[6:7], v[156:157] op_sel_hi:[1,0]
	v_pk_fma_f32 v[168:169], v[84:85], v[168:169], v[68:69]
	v_pk_fma_f32 v[170:171], v[86:87], v[170:171], v[70:71]
	v_cvt_pk_bf16_f32 v168, v168, v169
	v_cvt_pk_bf16_f32 v169, v170, v171
	global_store_dwordx2 v[158:159], v[168:169], off offset:512
	v_pk_mul_f32 v[168:169], v[8:9], v[156:157] op_sel_hi:[1,0]
	v_pk_mul_f32 v[170:171], v[10:11], v[156:157] op_sel_hi:[1,0]
	v_pk_fma_f32 v[168:169], v[88:89], v[168:169], v[72:73]
	v_pk_fma_f32 v[170:171], v[90:91], v[170:171], v[74:75]
	v_cvt_pk_bf16_f32 v168, v168, v169
	v_cvt_pk_bf16_f32 v169, v170, v171
	global_store_dwordx2 v[158:159], v[168:169], off offset:1024
	v_pk_mul_f32 v[168:169], v[12:13], v[156:157] op_sel_hi:[1,0]
	v_pk_mul_f32 v[156:157], v[14:15], v[156:157] op_sel_hi:[1,0]
	v_pk_fma_f32 v[168:169], v[92:93], v[168:169], v[76:77]
	v_pk_fma_f32 v[156:157], v[94:95], v[156:157], v[78:79]
	v_cvt_pk_bf16_f32 v168, v168, v169
	v_cvt_pk_bf16_f32 v169, v156, v157
	v_add_u32_e32 v156, -5, v140
	global_store_dwordx2 v[158:159], v[168:169], off offset:1536
	v_cmp_lt_i32_e32 vcc, v156, v123
	v_add_u32_e32 v168, -2, v140
	s_and_saveexec_b64 s[16:17], vcc
	s_cbranch_execz .LBB0_1170
	v_cmp_lt_i32_e32 vcc, v168, v123
	s_and_saveexec_b64 s[24:25], vcc
	s_cbranch_execz .LBB0_1167
	v_lshl_add_u64 v[0:1], v[138:139], 0, v[136:137]
	v_add_co_u32_e32 v104, vcc, 0x154bc000, v0
	s_nop 1
	v_addc_co_u32_e32 v105, vcc, 0, v1, vcc
	global_load_dwordx4 v[0:3], v[142:143], off offset:-3072 nt
	global_load_dwordx4 v[4:7], v[142:143], off offset:-2048 nt
	global_load_dwordx4 v[8:11], v[142:143], off offset:-1024 nt
	global_load_dwordx4 v[12:15], v[142:143], off nt
	global_load_dwordx2 v[98:99], v[104:105], off
	global_load_dwordx2 v[100:101], v[104:105], off offset:512
	global_load_dwordx2 v[102:103], v[104:105], off offset:1024
	s_nop 0
	global_load_dwordx2 v[104:105], v[104:105], off offset:1536
.LBB0_1167:
	s_or_b64 exec, exec, s[24:25]
	v_ashrrev_i32_e32 v141, 12, v156
	v_cmp_ne_u32_e32 vcc, v141, v167
	s_and_saveexec_b64 s[24:25], vcc
	s_cbranch_execz .LBB0_1169
	v_mul_hi_i32_i24_e32 v65, 0x6000, v141
	v_mul_i32_i24_e32 v64, 0x6000, v141
	v_lshl_add_u64 v[64:65], s[88:89], 0, v[64:65]
	v_lshl_add_u64 v[66:67], v[64:65], 0, s[10:11]
	v_lshlrev_b32_e32 v68, 2, v122
	v_mov_b32_e32 v69, v97
	v_lshl_add_u64 v[76:77], v[64:65], 0, s[12:13]
	v_lshl_add_u64 v[64:65], v[66:67], 0, v[96:97]
	v_lshl_add_u64 v[70:71], v[66:67], 0, v[68:69]
	v_lshlrev_b32_e32 v72, 2, v124
	v_mov_b32_e32 v73, v97
	global_load_dwordx4 v[80:83], v[64:65], off nt
	global_load_dwordx4 v[84:87], v[70:71], off nt
	v_lshl_add_u64 v[70:71], v[66:67], 0, v[72:73]
	v_lshlrev_b32_e32 v78, 2, v126
	v_mov_b32_e32 v79, v97
	v_lshl_add_u64 v[64:65], v[76:77], 0, v[96:97]
	global_load_dwordx4 v[88:91], v[70:71], off nt
	v_lshl_add_u64 v[66:67], v[66:67], 0, v[78:79]
	v_lshl_add_u64 v[68:69], v[76:77], 0, v[68:69]
	global_load_dwordx4 v[92:95], v[66:67], off nt
	s_nop 0
	global_load_dwordx4 v[64:67], v[64:65], off nt
	s_nop 0
	global_load_dwordx4 v[170:173], v[130:131], off nt
	global_load_dwordx4 v[174:177], v[130:131], off offset:1024 nt
	s_nop 0
	global_load_dwordx4 v[68:71], v[68:69], off nt
	s_nop 0
	global_load_dwordx4 v[178:181], v[130:131], off offset:2048 nt
	v_lshl_add_u64 v[72:73], v[76:77], 0, v[72:73]
	v_lshl_add_u64 v[76:77], v[76:77], 0, v[78:79]
	global_load_dwordx4 v[182:185], v[130:131], off offset:3072 nt
	s_nop 0
	global_load_dwordx4 v[72:75], v[72:73], off nt
	v_mov_b32_e32 v167, v141
	global_load_dwordx4 v[76:79], v[76:77], off nt
	s_waitcnt vmcnt(11)
	v_pk_add_f32 v[82:83], v[82:83], 1.0 op_sel_hi:[1,0]
	v_pk_add_f32 v[80:81], v[80:81], 1.0 op_sel_hi:[1,0]
	s_waitcnt vmcnt(10)
	v_pk_add_f32 v[86:87], v[86:87], 1.0 op_sel_hi:[1,0]
	v_pk_add_f32 v[84:85], v[84:85], 1.0 op_sel_hi:[1,0]
	s_waitcnt vmcnt(9)
	v_pk_add_f32 v[90:91], v[90:91], 1.0 op_sel_hi:[1,0]
	v_pk_add_f32 v[88:89], v[88:89], 1.0 op_sel_hi:[1,0]
	s_waitcnt vmcnt(8)
	v_pk_add_f32 v[94:95], v[94:95], 1.0 op_sel_hi:[1,0]
	v_pk_add_f32 v[92:93], v[92:93], 1.0 op_sel_hi:[1,0]
	s_waitcnt vmcnt(6)
	v_pk_mul_f32 v[82:83], v[172:173], v[82:83]
	v_pk_mul_f32 v[80:81], v[170:171], v[80:81]
	s_waitcnt vmcnt(5)
	v_pk_mul_f32 v[86:87], v[176:177], v[86:87]
	v_pk_mul_f32 v[84:85], v[174:175], v[84:85]
	s_waitcnt vmcnt(3)
	v_pk_mul_f32 v[90:91], v[180:181], v[90:91]
	v_pk_mul_f32 v[88:89], v[178:179], v[88:89]
	s_waitcnt vmcnt(2)
	v_pk_mul_f32 v[94:95], v[184:185], v[94:95]
	v_pk_mul_f32 v[92:93], v[182:183], v[92:93]

.LBB0_1170:
	s_or_b64 exec, exec, s[16:17]
	v_add_u32_e32 v156, -4, v140
	v_cmp_lt_i32_e32 vcc, v156, v123
	s_and_saveexec_b64 s[16:17], vcc
	s_cbranch_execz .LBB0_1176
	v_add_u32_e32 v158, -1, v140
	v_cmp_lt_i32_e32 vcc, v158, v123
	s_and_saveexec_b64 s[24:25], vcc
	s_cbranch_execz .LBB0_1173
	v_ashrrev_i32_e32 v159, 31, v158
	v_lshlrev_b64 v[16:17], 12, v[158:159]
	v_lshl_add_u64 v[28:29], v[132:133], 0, v[16:17]
	v_lshlrev_b64 v[16:17], 11, v[158:159]
	v_lshl_add_u64 v[112:113], v[134:135], 0, v[16:17]
	global_load_dwordx4 v[16:19], v[28:29], off nt
	global_load_dwordx4 v[20:23], v[28:29], off offset:1024 nt
	global_load_dwordx4 v[24:27], v[28:29], off offset:2048 nt
	s_nop 0
	global_load_dwordx4 v[28:31], v[28:29], off offset:3072 nt
	s_nop 0
	global_load_dwordx2 v[106:107], v[112:113], off
	global_load_dwordx2 v[108:109], v[112:113], off offset:512
	global_load_dwordx2 v[110:111], v[112:113], off offset:1024
	s_nop 0
	global_load_dwordx2 v[112:113], v[112:113], off offset:1536

.LBB0_1176:
	s_or_b64 exec, exec, s[16:17]
	s_and_saveexec_b64 s[16:17], s[4:5]
	s_cbranch_execz .LBB0_1159
	v_cmp_lt_i32_e32 vcc, v140, v123
	s_and_saveexec_b64 s[4:5], vcc
	s_cbranch_execz .LBB0_1179
	v_ashrrev_i32_e32 v141, 31, v140
	v_lshlrev_b64 v[32:33], 12, v[140:141]
	v_lshl_add_u64 v[44:45], v[132:133], 0, v[32:33]
	v_lshlrev_b64 v[32:33], 11, v[140:141]
	v_lshl_add_u64 v[120:121], v[134:135], 0, v[32:33]
	global_load_dwordx4 v[32:35], v[44:45], off nt
	global_load_dwordx4 v[36:39], v[44:45], off offset:1024 nt
	global_load_dwordx4 v[40:43], v[44:45], off offset:2048 nt
	s_nop 0
	global_load_dwordx4 v[44:47], v[44:45], off offset:3072 nt
	s_nop 0
	global_load_dwordx2 v[114:115], v[120:121], off
	global_load_dwordx2 v[116:117], v[120:121], off offset:512
	global_load_dwordx2 v[118:119], v[120:121], off offset:1024
	s_nop 0
	global_load_dwordx2 v[120:121], v[120:121], off offset:1536
.LBB0_1179:
	s_or_b64 exec, exec, s[4:5]
	v_ashrrev_i32_e32 v141, 12, v154
	v_cmp_ne_u32_e32 vcc, v141, v167
	s_and_saveexec_b64 s[4:5], vcc
	s_cbranch_execz .LBB0_1158
	v_mul_hi_i32_i24_e32 v65, 0x6000, v141
	v_mul_i32_i24_e32 v64, 0x6000, v141
	v_lshl_add_u64 v[64:65], s[88:89], 0, v[64:65]
	v_lshl_add_u64 v[66:67], v[64:65], 0, s[10:11]
	v_lshlrev_b32_e32 v68, 2, v122
	v_mov_b32_e32 v69, v97
	v_lshl_add_u64 v[76:77], v[64:65], 0, s[12:13]
	v_lshl_add_u64 v[64:65], v[66:67], 0, v[96:97]
	v_lshl_add_u64 v[70:71], v[66:67], 0, v[68:69]
	v_lshlrev_b32_e32 v72, 2, v124
	v_mov_b32_e32 v73, v97
	global_load_dwordx4 v[80:83], v[64:65], off nt
	global_load_dwordx4 v[84:87], v[70:71], off nt
	v_lshl_add_u64 v[70:71], v[66:67], 0, v[72:73]
	v_lshlrev_b32_e32 v78, 2, v126
	v_mov_b32_e32 v79, v97
	v_lshl_add_u64 v[64:65], v[76:77], 0, v[96:97]
	global_load_dwordx4 v[88:91], v[70:71], off nt
	v_lshl_add_u64 v[66:67], v[66:67], 0, v[78:79]
	v_lshl_add_u64 v[68:69], v[76:77], 0, v[68:69]
	global_load_dwordx4 v[92:95], v[66:67], off nt
	s_nop 0
	global_load_dwordx4 v[64:67], v[64:65], off nt
	s_nop 0
	global_load_dwordx4 v[156:159], v[130:131], off nt
	global_load_dwordx4 v[170:173], v[130:131], off offset:1024 nt
	s_nop 0
	global_load_dwordx4 v[68:71], v[68:69], off nt
	s_nop 0
	global_load_dwordx4 v[174:177], v[130:131], off offset:2048 nt
	v_lshl_add_u64 v[72:73], v[76:77], 0, v[72:73]
	v_lshl_add_u64 v[76:77], v[76:77], 0, v[78:79]
	global_load_dwordx4 v[178:181], v[130:131], off offset:3072 nt
	s_nop 0
	global_load_dwordx4 v[72:75], v[72:73], off nt
	v_mov_b32_e32 v167, v141
	global_load_dwordx4 v[76:79], v[76:77], off nt
	s_waitcnt vmcnt(11)
	v_pk_add_f32 v[82:83], v[82:83], 1.0 op_sel_hi:[1,0]
	v_pk_add_f32 v[80:81], v[80:81], 1.0 op_sel_hi:[1,0]
	s_waitcnt vmcnt(10)
	v_pk_add_f32 v[86:87], v[86:87], 1.0 op_sel_hi:[1,0]
	v_pk_add_f32 v[84:85], v[84:85], 1.0 op_sel_hi:[1,0]
	s_waitcnt vmcnt(9)
	v_pk_add_f32 v[90:91], v[90:91], 1.0 op_sel_hi:[1,0]
	v_pk_add_f32 v[88:89], v[88:89], 1.0 op_sel_hi:[1,0]
	s_waitcnt vmcnt(8)
	v_pk_add_f32 v[94:95], v[94:95], 1.0 op_sel_hi:[1,0]
	v_pk_add_f32 v[92:93], v[92:93], 1.0 op_sel_hi:[1,0]
	s_waitcnt vmcnt(6)
	v_pk_mul_f32 v[82:83], v[158:159], v[82:83]
	v_pk_mul_f32 v[80:81], v[156:157], v[80:81]
	s_waitcnt vmcnt(5)
	v_pk_mul_f32 v[86:87], v[172:173], v[86:87]
	v_pk_mul_f32 v[84:85], v[170:171], v[84:85]
	s_waitcnt vmcnt(3)
	v_pk_mul_f32 v[90:91], v[176:177], v[90:91]
	v_pk_mul_f32 v[88:89], v[174:175], v[88:89]
	s_waitcnt vmcnt(2)
	v_pk_mul_f32 v[94:95], v[180:181], v[94:95]
	v_pk_mul_f32 v[92:93], v[178:179], v[92:93]
	s_branch .LBB0_1158
